# v30: v22 + attention tile loop: branch-free source-row select for the tile-(i+2) loads, rescale block moved out of line (common path falls through)
# baseline (speedup 1.0000x reference)
; template <int PM> DI void attn_phase(const Params& p, int l, char* smem, int* s_item, int wv, int cidx) {
;     ...
;         if (PM != 2 && i + 2 < ntl) {
;           const int inx = i + 2;
;           const int Rn = (inx < nplain) ? Rb + 64 * inx : Rb + 256 + local_t0 + 64 * (inx - nplain);
;           const u16* nbase = p.P + (size_t)(Rn + trow) * INW + tch * 8;
; #pragma unroll
;           for (int j = 0; j < 2; ++j) {
;             kst[j] = *(const u32x4*)(nbase + (size_t)j * 32 * INW + koff);
;             vst[j] = *(const u32x4*)(nbase + (size_t)j * 32 * INW + voff);
;           }
;         }
.LBB0_424:
	s_add_i32 s3, s2, 2
	s_cmp_ge_i32 s3, s81
	s_cbranch_scc1 .LBB0_430
	s_lshl_b32 s0, s3, 6
	s_add_i32 s0, s0, s84
	s_add_i32 s74, s90, s92
	s_cmp_ge_u32 s3, s80
	s_cselect_b32 s74, s74, s0

; DI float fexp2(float x) { return __builtin_amdgcn_exp2f(x); }
; DI float half_max(float v) { const auto r = __builtin_amdgcn_permlane32_swap(__float_as_uint(v), __float_as_uint(v), false, false); return fmaxf(__uint_as_float(r[0]), __uint_as_float(r[1])); }
; template <int PM> DI void attn_phase(const Params& p, int l, char* smem, int* s_item, int wv, int cidx) {
;     ...
;           float mt = sacc[0][0];
; #pragma unroll
;           for (int e = 1; e < 16; ++e) mt = fmaxf(mt, sacc[0][e]);
; #pragma unroll
;           for (int e = 0; e < 16; ++e) mt = fmaxf(mt, sacc[1][e]);
;           mt = half_max(mt);
;           if (__builtin_amdgcn_ballot_w64(mt > m + 8.f) != 0ull) {
;             const float mnew = fmaxf(m, mt);
;             const float alpha = fexp2(m - mnew);
;             m = mnew;
.LBB0_512:
	v_max_f32_e32 v0, v17, v17
	s_waitcnt lgkmcnt(2)
	v_max_f32_e32 v2, v16, v16
	v_max_f32_e32 v0, v2, v0
	v_max3_f32 v0, v0, v18, v19
	v_max3_f32 v0, v0, v20, v21
	v_max3_f32 v0, v0, v22, v23
	v_max3_f32 v0, v0, v24, v25
	v_max3_f32 v0, v0, v26, v27
	v_max3_f32 v0, v0, v28, v29
	v_max3_f32 v0, v0, v30, v31
	v_max3_f32 v0, v0, v32, v33
	v_max3_f32 v0, v0, v34, v35
	v_max3_f32 v0, v0, v36, v37
	v_max3_f32 v0, v0, v38, v39
	v_max3_f32 v0, v0, v40, v41
	v_max3_f32 v0, v0, v42, v43
	v_max3_f32 v0, v0, v44, v45
	v_max3_f32 v0, v0, v46, v47
	v_mov_b32_e32 v2, v0
	s_nop 1
	v_permlane32_swap_b32_e32 v0, v2
	v_max_f32_e32 v2, v2, v2
	v_max_f32_e32 v0, v0, v0
	v_max_f32_e32 v0, v0, v2
	v_add_f32_e32 v2, 0x41000000, v233
	v_cmp_gt_f32_e32 vcc, v0, v2
	s_cbranch_vccnz .Lst_resc

; DI float fexp2(float x) { return __builtin_amdgcn_exp2f(x); }
; template <int PM> DI void attn_phase(const Params& p, int l, char* smem, int* s_item, int wv, int cidx) {
;     ...
;           if (__builtin_amdgcn_ballot_w64(mt > m + 8.f) != 0ull) {
;             const float mnew = fmaxf(m, mt);
;             const float alpha = fexp2(m - mnew);
;             m = mnew;
;             lsum *= alpha;
; #pragma unroll
;             for (int db = 0; db < 4; ++db)
; #pragma unroll
;               for (int e = 0; e < 16; ++e) Oacc[db][e] *= alpha;
;           }
.Lst_resc:
	v_max_f32_e32 v0, v0, v0
	v_max_f32_e32 v2, v233, v233
	v_max_f32_e32 v2, v2, v0
	v_sub_f32_e32 v0, v233, v2
	v_exp_f32_e32 v0, v0
	v_mov_b32_e32 v233, v2
	v_pk_mul_f32 v[142:143], v[142:143], v[0:1] op_sel_hi:[1,0]
	v_pk_mul_f32 v[140:141], v[140:141], v[0:1] op_sel_hi:[1,0]
	v_pk_mul_f32 v[138:139], v[138:139], v[0:1] op_sel_hi:[1,0]
	v_pk_mul_f32 v[136:137], v[136:137], v[0:1] op_sel_hi:[1,0]
	v_pk_mul_f32 v[134:135], v[134:135], v[0:1] op_sel_hi:[1,0]
	v_pk_mul_f32 v[132:133], v[132:133], v[0:1] op_sel_hi:[1,0]
	v_pk_mul_f32 v[130:131], v[130:131], v[0:1] op_sel_hi:[1,0]
	v_pk_mul_f32 v[128:129], v[128:129], v[0:1] op_sel_hi:[1,0]
	v_pk_mul_f32 v[126:127], v[126:127], v[0:1] op_sel_hi:[1,0]
	v_pk_mul_f32 v[124:125], v[124:125], v[0:1] op_sel_hi:[1,0]
	v_pk_mul_f32 v[122:123], v[122:123], v[0:1] op_sel_hi:[1,0]
	v_pk_mul_f32 v[120:121], v[120:121], v[0:1] op_sel_hi:[1,0]
	v_pk_mul_f32 v[118:119], v[118:119], v[0:1] op_sel_hi:[1,0]
	v_pk_mul_f32 v[116:117], v[116:117], v[0:1] op_sel_hi:[1,0]
	v_pk_mul_f32 v[114:115], v[114:115], v[0:1] op_sel_hi:[1,0]
	v_pk_mul_f32 v[112:113], v[112:113], v[0:1] op_sel_hi:[1,0]
	v_pk_mul_f32 v[110:111], v[110:111], v[0:1] op_sel_hi:[1,0]
	v_pk_mul_f32 v[108:109], v[108:109], v[0:1] op_sel_hi:[1,0]
	v_pk_mul_f32 v[106:107], v[106:107], v[0:1] op_sel_hi:[1,0]
	v_pk_mul_f32 v[104:105], v[104:105], v[0:1] op_sel_hi:[1,0]
	v_pk_mul_f32 v[102:103], v[102:103], v[0:1] op_sel_hi:[1,0]
	v_pk_mul_f32 v[100:101], v[100:101], v[0:1] op_sel_hi:[1,0]
	v_pk_mul_f32 v[98:99], v[98:99], v[0:1] op_sel_hi:[1,0]
	v_pk_mul_f32 v[96:97], v[96:97], v[0:1] op_sel_hi:[1,0]
	v_pk_mul_f32 v[94:95], v[94:95], v[0:1] op_sel_hi:[1,0]
	v_pk_mul_f32 v[92:93], v[92:93], v[0:1] op_sel_hi:[1,0]
	v_pk_mul_f32 v[90:91], v[90:91], v[0:1] op_sel_hi:[1,0]
	v_pk_mul_f32 v[88:89], v[88:89], v[0:1] op_sel_hi:[1,0]
	v_pk_mul_f32 v[86:87], v[86:87], v[0:1] op_sel_hi:[1,0]
	v_pk_mul_f32 v[84:85], v[84:85], v[0:1] op_sel_hi:[1,0]
	v_pk_mul_f32 v[82:83], v[82:83], v[0:1] op_sel_hi:[1,0]
	v_pk_mul_f32 v[80:81], v[80:81], v[0:1] op_sel_hi:[1,0]
	v_mul_f32_e32 v235, v235, v0
	s_branch .LBB0_514
